# rglru: hand-scheduled tile loop (hoisted Wt fragments, batched LDS reads, 8 interleaved token chains, single 16-tile loop) on top of batched prologue
# speedup vs baseline: 1.0072x; 1.0072x over previous
.LBB0_324:
	s_waitcnt vmcnt(0)
	v_mov_b32_e32 v20, v216
	s_bfe_u32 s6, s24, 0x30002
	s_lshl_b32 s0, s24, 4
	s_and_b32 s10, s0, 48
	s_lshl_b32 s11, s6, 12
	s_or_b32 s11, s11, s10
	s_lshl_b32 s12, s6, 6
	v_mov_b32_e32 v36, s11
	v_mov_b32_e32 v0, s12
	v_and_b32_e32 v1, 63, v20
	v_lshrrev_b32_e32 v4, 6, v20
	v_lshl_add_u32 v5, v1, 6, v4
	v_add_lshl_u32 v168, v5, s11, 2
	v_lshl_add_u64 v[6:7], s[2:3], 0, v[168:169]
	v_lshl_add_u64 v[8:9], s[22:23], 0, v[168:169]
	global_load_dword v10, v[6:7], off
	global_load_dword v11, v[6:7], off offset:32
	global_load_dword v12, v[8:9], off
	global_load_dword v13, v[8:9], off offset:32
	v_add_lshl_u32 v168, v1, s12, 2
	v_lshl_add_u64 v[6:7], s[26:27], 0, v[168:169]
	v_add_co_u32_e32 v8, vcc, 0x1000, v6
	s_nop 1
	v_addc_co_u32_e32 v9, vcc, 0, v7, vcc
	global_load_dword v14, v[6:7], off
	global_load_dword v15, v[6:7], off offset:2048
	global_load_dword v16, v[8:9], off
	global_load_dword v17, v[8:9], off offset:2048
	v_and_b32_e32 v34, 15, v20
	v_or_b32_e32 v21, s10, v34
	v_or_b32_e32 v26, v21, v0
	v_mov_b32_e32 v27, v169
	v_readlane_b32 s0, v246, 45
	v_lshlrev_b64 v[2:3], 2, v[26:27]
	v_readlane_b32 s1, v246, 46
	v_readlane_b32 s4, v246, 47
	v_readlane_b32 s5, v246, 48
	s_nop 3
	v_lshl_add_u64 v[28:29], s[0:1], 0, v[2:3]
	v_lshl_add_u64 v[30:31], s[4:5], 0, v[2:3]
	global_load_dword v24, v[28:29], off
	global_load_dword v25, v[30:31], off
	v_readlane_b32 s0, v246, 43
	v_readlane_b32 s1, v246, 44
	s_lshl_b32 s30, s6, 8
	s_nop 3
	s_add_u32 s0, s0, s30
	s_addc_u32 s1, s1, 0
	s_load_dwordx16 s[48:63], s[0:1], 0x0
	s_load_dwordx16 s[64:79], s[0:1], 0x40
	s_load_dwordx16 s[80:95], s[0:1], 0x80
	v_add_lshl_u32 v168, v36, v34, 2
	v_lshl_add_u64 v[4:5], s[2:3], 0, v[168:169]
	v_lshl_add_u64 v[6:7], s[22:23], 0, v[168:169]
	global_load_dword v40, v[4:5], off
	global_load_dword v56, v[6:7], off
	global_load_dword v41, v[4:5], off offset:256
	global_load_dword v57, v[6:7], off offset:256
	global_load_dword v42, v[4:5], off offset:512
	global_load_dword v58, v[6:7], off offset:512
	global_load_dword v43, v[4:5], off offset:768
	global_load_dword v59, v[6:7], off offset:768
	global_load_dword v44, v[4:5], off offset:1024
	global_load_dword v60, v[6:7], off offset:1024
	global_load_dword v45, v[4:5], off offset:1280
	global_load_dword v61, v[6:7], off offset:1280
	global_load_dword v46, v[4:5], off offset:1536
	global_load_dword v62, v[6:7], off offset:1536
	global_load_dword v47, v[4:5], off offset:1792
	global_load_dword v63, v[6:7], off offset:1792
	global_load_dword v48, v[4:5], off offset:2048
	global_load_dword v64, v[6:7], off offset:2048
	global_load_dword v49, v[4:5], off offset:2304
	global_load_dword v65, v[6:7], off offset:2304
	global_load_dword v50, v[4:5], off offset:2560
	global_load_dword v66, v[6:7], off offset:2560
	global_load_dword v51, v[4:5], off offset:2816
	global_load_dword v67, v[6:7], off offset:2816
	global_load_dword v52, v[4:5], off offset:3072
	global_load_dword v68, v[6:7], off offset:3072
	global_load_dword v53, v[4:5], off offset:3328
	global_load_dword v69, v[6:7], off offset:3328
	global_load_dword v54, v[4:5], off offset:3584
	global_load_dword v70, v[6:7], off offset:3584
	global_load_dword v55, v[4:5], off offset:3840
	global_load_dword v71, v[6:7], off offset:3840
	v_add_co_u32_e32 v4, vcc, 0x1000, v4
	s_nop 1
	v_addc_co_u32_e32 v5, vcc, 0, v5, vcc
	v_add_co_u32_e32 v6, vcc, 0x1000, v6
	s_nop 1
	v_addc_co_u32_e32 v7, vcc, 0, v7, vcc
	v_lshrrev_b32_e32 v18, 6, v20
	v_mul_u32_u24_e32 v18, 0x90, v18
	v_lshl_add_u32 v18, v1, 1, v18
	s_waitcnt vmcnt(34)
	v_mul_f32_e32 v22, v10, v14
	v_mul_f32_e32 v23, v11, v14
	v_cvt_pk_bf16_f32 v22, v22, v23
	ds_write_b16 v18, v22 offset:37440
	ds_write_b16_d16_hi v18, v22 offset:38592
	v_mul_f32_e32 v22, v12, v14
	v_mul_f32_e32 v23, v13, v14
	v_cvt_pk_bf16_f32 v22, v22, v23
	ds_write_b16 v18, v22 offset:39744
	ds_write_b16_d16_hi v18, v22 offset:40896
	v_mul_f32_e32 v22, v10, v15
	v_mul_f32_e32 v23, v11, v15
	v_cvt_pk_bf16_f32 v22, v22, v23
	ds_write_b16 v18, v22 offset:42048
	ds_write_b16_d16_hi v18, v22 offset:43200
	v_mul_f32_e32 v22, v12, v15
	v_mul_f32_e32 v23, v13, v15
	v_cvt_pk_bf16_f32 v22, v22, v23
	ds_write_b16 v18, v22 offset:44352
	ds_write_b16_d16_hi v18, v22 offset:45504
	v_mul_f32_e32 v22, v10, v16
	v_mul_f32_e32 v23, v11, v16
	v_cvt_pk_bf16_f32 v22, v22, v23
	ds_write_b16 v18, v22 offset:46656
	ds_write_b16_d16_hi v18, v22 offset:47808
	v_mul_f32_e32 v22, v12, v16
	v_mul_f32_e32 v23, v13, v16
	v_cvt_pk_bf16_f32 v22, v22, v23
	ds_write_b16 v18, v22 offset:48960
	ds_write_b16_d16_hi v18, v22 offset:50112
	v_mul_f32_e32 v22, v10, v17
	v_mul_f32_e32 v23, v11, v17
	v_cvt_pk_bf16_f32 v22, v22, v23
	ds_write_b16 v18, v22 offset:51264
	ds_write_b16_d16_hi v18, v22 offset:52416
	v_mul_f32_e32 v22, v12, v17
	v_mul_f32_e32 v23, v13, v17
	v_cvt_pk_bf16_f32 v22, v22, v23
	ds_write_b16 v18, v22 offset:53568
	ds_write_b16_d16_hi v18, v22 offset:54720
	s_waitcnt vmcnt(0) lgkmcnt(0)
	global_load_dword v72, v[4:5], off
	global_load_dword v88, v[6:7], off
	global_load_dword v73, v[4:5], off offset:256
	global_load_dword v89, v[6:7], off offset:256
	global_load_dword v74, v[4:5], off offset:512
	global_load_dword v90, v[6:7], off offset:512
	global_load_dword v75, v[4:5], off offset:768
	global_load_dword v91, v[6:7], off offset:768
	global_load_dword v76, v[4:5], off offset:1024
	global_load_dword v92, v[6:7], off offset:1024
	global_load_dword v77, v[4:5], off offset:1280
	global_load_dword v93, v[6:7], off offset:1280
	global_load_dword v78, v[4:5], off offset:1536
	global_load_dword v94, v[6:7], off offset:1536
	global_load_dword v79, v[4:5], off offset:1792
	global_load_dword v95, v[6:7], off offset:1792
	global_load_dword v80, v[4:5], off offset:2048
	global_load_dword v96, v[6:7], off offset:2048
	global_load_dword v81, v[4:5], off offset:2304
	global_load_dword v97, v[6:7], off offset:2304
	global_load_dword v82, v[4:5], off offset:2560
	global_load_dword v98, v[6:7], off offset:2560
	global_load_dword v83, v[4:5], off offset:2816
	global_load_dword v99, v[6:7], off offset:2816
	global_load_dword v84, v[4:5], off offset:3072
	global_load_dword v100, v[6:7], off offset:3072
	global_load_dword v85, v[4:5], off offset:3328
	global_load_dword v101, v[6:7], off offset:3328
	global_load_dword v86, v[4:5], off offset:3584
	global_load_dword v102, v[6:7], off offset:3584
	global_load_dword v87, v[4:5], off offset:3840
	global_load_dword v103, v[6:7], off offset:3840
	v_add_co_u32_e32 v4, vcc, 0x1000, v4
	s_nop 1
	v_addc_co_u32_e32 v5, vcc, 0, v5, vcc
	v_add_co_u32_e32 v6, vcc, 0x1000, v6
	s_nop 1
	v_addc_co_u32_e32 v7, vcc, 0, v7, vcc
	v_fma_f32 v24, s48, v40, v24
	v_fma_f32 v25, s48, v56, v25
	v_fma_f32 v24, s49, v41, v24
	v_fma_f32 v25, s49, v57, v25
	v_fma_f32 v24, s50, v42, v24
	v_fma_f32 v25, s50, v58, v25
	v_fma_f32 v24, s51, v43, v24
	v_fma_f32 v25, s51, v59, v25
	v_fma_f32 v24, s52, v44, v24
	v_fma_f32 v25, s52, v60, v25
	v_fma_f32 v24, s53, v45, v24
	v_fma_f32 v25, s53, v61, v25
	v_fma_f32 v24, s54, v46, v24
	v_fma_f32 v25, s54, v62, v25
	v_fma_f32 v24, s55, v47, v24
	v_fma_f32 v25, s55, v63, v25
	v_fma_f32 v24, s56, v48, v24
	v_fma_f32 v25, s56, v64, v25
	v_fma_f32 v24, s57, v49, v24
	v_fma_f32 v25, s57, v65, v25
	v_fma_f32 v24, s58, v50, v24
	v_fma_f32 v25, s58, v66, v25
	v_fma_f32 v24, s59, v51, v24
	v_fma_f32 v25, s59, v67, v25
	v_fma_f32 v24, s60, v52, v24
	v_fma_f32 v25, s60, v68, v25
	v_fma_f32 v24, s61, v53, v24
	v_fma_f32 v25, s61, v69, v25
	v_fma_f32 v24, s62, v54, v24
	v_fma_f32 v25, s62, v70, v25
	v_fma_f32 v24, s63, v55, v24
	v_fma_f32 v25, s63, v71, v25
	s_load_dwordx16 s[48:63], s[0:1], 0xc0
	s_waitcnt vmcnt(0)
	global_load_dword v40, v[4:5], off
	global_load_dword v56, v[6:7], off
	global_load_dword v41, v[4:5], off offset:256
	global_load_dword v57, v[6:7], off offset:256
	global_load_dword v42, v[4:5], off offset:512
	global_load_dword v58, v[6:7], off offset:512
	global_load_dword v43, v[4:5], off offset:768
	global_load_dword v59, v[6:7], off offset:768
	global_load_dword v44, v[4:5], off offset:1024
	global_load_dword v60, v[6:7], off offset:1024
	global_load_dword v45, v[4:5], off offset:1280
	global_load_dword v61, v[6:7], off offset:1280
	global_load_dword v46, v[4:5], off offset:1536
	global_load_dword v62, v[6:7], off offset:1536
	global_load_dword v47, v[4:5], off offset:1792
	global_load_dword v63, v[6:7], off offset:1792
	global_load_dword v48, v[4:5], off offset:2048
	global_load_dword v64, v[6:7], off offset:2048
	global_load_dword v49, v[4:5], off offset:2304
	global_load_dword v65, v[6:7], off offset:2304
	global_load_dword v50, v[4:5], off offset:2560
	global_load_dword v66, v[6:7], off offset:2560
	global_load_dword v51, v[4:5], off offset:2816
	global_load_dword v67, v[6:7], off offset:2816
	global_load_dword v52, v[4:5], off offset:3072
	global_load_dword v68, v[6:7], off offset:3072
	global_load_dword v53, v[4:5], off offset:3328
	global_load_dword v69, v[6:7], off offset:3328
	global_load_dword v54, v[4:5], off offset:3584
	global_load_dword v70, v[6:7], off offset:3584
	global_load_dword v55, v[4:5], off offset:3840
	global_load_dword v71, v[6:7], off offset:3840
	v_add_co_u32_e32 v4, vcc, 0x1000, v4
	s_nop 1
	v_addc_co_u32_e32 v5, vcc, 0, v5, vcc
	v_add_co_u32_e32 v6, vcc, 0x1000, v6
	s_nop 1
	v_addc_co_u32_e32 v7, vcc, 0, v7, vcc
	v_fma_f32 v24, s64, v72, v24
	v_fma_f32 v25, s64, v88, v25
	v_fma_f32 v24, s65, v73, v24
	v_fma_f32 v25, s65, v89, v25
	v_fma_f32 v24, s66, v74, v24
	v_fma_f32 v25, s66, v90, v25
	v_fma_f32 v24, s67, v75, v24
	v_fma_f32 v25, s67, v91, v25
	v_fma_f32 v24, s68, v76, v24
	v_fma_f32 v25, s68, v92, v25
	v_fma_f32 v24, s69, v77, v24
	v_fma_f32 v25, s69, v93, v25
	v_fma_f32 v24, s70, v78, v24
	v_fma_f32 v25, s70, v94, v25
	v_fma_f32 v24, s71, v79, v24
	v_fma_f32 v25, s71, v95, v25
	v_fma_f32 v24, s72, v80, v24
	v_fma_f32 v25, s72, v96, v25
	v_fma_f32 v24, s73, v81, v24
	v_fma_f32 v25, s73, v97, v25
	v_fma_f32 v24, s74, v82, v24
	v_fma_f32 v25, s74, v98, v25
	v_fma_f32 v24, s75, v83, v24
	v_fma_f32 v25, s75, v99, v25
	v_fma_f32 v24, s76, v84, v24
	v_fma_f32 v25, s76, v100, v25
	v_fma_f32 v24, s77, v85, v24
	v_fma_f32 v25, s77, v101, v25
	v_fma_f32 v24, s78, v86, v24
	v_fma_f32 v25, s78, v102, v25
	v_fma_f32 v24, s79, v87, v24
	v_fma_f32 v25, s79, v103, v25
	s_waitcnt vmcnt(0)
	global_load_dword v72, v[4:5], off
	global_load_dword v88, v[6:7], off
	global_load_dword v73, v[4:5], off offset:256
	global_load_dword v89, v[6:7], off offset:256
	global_load_dword v74, v[4:5], off offset:512
	global_load_dword v90, v[6:7], off offset:512
	global_load_dword v75, v[4:5], off offset:768
	global_load_dword v91, v[6:7], off offset:768
	global_load_dword v76, v[4:5], off offset:1024
	global_load_dword v92, v[6:7], off offset:1024
	global_load_dword v77, v[4:5], off offset:1280
	global_load_dword v93, v[6:7], off offset:1280
	global_load_dword v78, v[4:5], off offset:1536
	global_load_dword v94, v[6:7], off offset:1536
	global_load_dword v79, v[4:5], off offset:1792
	global_load_dword v95, v[6:7], off offset:1792
	global_load_dword v80, v[4:5], off offset:2048
	global_load_dword v96, v[6:7], off offset:2048
	global_load_dword v81, v[4:5], off offset:2304
	global_load_dword v97, v[6:7], off offset:2304
	global_load_dword v82, v[4:5], off offset:2560
	global_load_dword v98, v[6:7], off offset:2560
	global_load_dword v83, v[4:5], off offset:2816
	global_load_dword v99, v[6:7], off offset:2816
	global_load_dword v84, v[4:5], off offset:3072
	global_load_dword v100, v[6:7], off offset:3072
	global_load_dword v85, v[4:5], off offset:3328
	global_load_dword v101, v[6:7], off offset:3328
	global_load_dword v86, v[4:5], off offset:3584
	global_load_dword v102, v[6:7], off offset:3584
	global_load_dword v87, v[4:5], off offset:3840
	global_load_dword v103, v[6:7], off offset:3840
	v_fma_f32 v24, s80, v40, v24
	v_fma_f32 v25, s80, v56, v25
	v_fma_f32 v24, s81, v41, v24
	v_fma_f32 v25, s81, v57, v25
	v_fma_f32 v24, s82, v42, v24
	v_fma_f32 v25, s82, v58, v25
	v_fma_f32 v24, s83, v43, v24
	v_fma_f32 v25, s83, v59, v25
	v_fma_f32 v24, s84, v44, v24
	v_fma_f32 v25, s84, v60, v25
	v_fma_f32 v24, s85, v45, v24
	v_fma_f32 v25, s85, v61, v25
	v_fma_f32 v24, s86, v46, v24
	v_fma_f32 v25, s86, v62, v25
	v_fma_f32 v24, s87, v47, v24
	v_fma_f32 v25, s87, v63, v25
	v_fma_f32 v24, s88, v48, v24
	v_fma_f32 v25, s88, v64, v25
	v_fma_f32 v24, s89, v49, v24
	v_fma_f32 v25, s89, v65, v25
	v_fma_f32 v24, s90, v50, v24
	v_fma_f32 v25, s90, v66, v25
	v_fma_f32 v24, s91, v51, v24
	v_fma_f32 v25, s91, v67, v25
	v_fma_f32 v24, s92, v52, v24
	v_fma_f32 v25, s92, v68, v25
	v_fma_f32 v24, s93, v53, v24
	v_fma_f32 v25, s93, v69, v25
	v_fma_f32 v24, s94, v54, v24
	v_fma_f32 v25, s94, v70, v25
	v_fma_f32 v24, s95, v55, v24
	v_fma_f32 v25, s95, v71, v25
	s_waitcnt vmcnt(0) lgkmcnt(0)
	v_fma_f32 v24, s48, v72, v24
	v_fma_f32 v25, s48, v88, v25
	v_fma_f32 v24, s49, v73, v24
	v_fma_f32 v25, s49, v89, v25
	v_fma_f32 v24, s50, v74, v24
	v_fma_f32 v25, s50, v90, v25
	v_fma_f32 v24, s51, v75, v24
	v_fma_f32 v25, s51, v91, v25
	v_fma_f32 v24, s52, v76, v24
	v_fma_f32 v25, s52, v92, v25
	v_fma_f32 v24, s53, v77, v24
	v_fma_f32 v25, s53, v93, v25
	v_fma_f32 v24, s54, v78, v24
	v_fma_f32 v25, s54, v94, v25
	v_fma_f32 v24, s55, v79, v24
	v_fma_f32 v25, s55, v95, v25
	v_fma_f32 v24, s56, v80, v24
	v_fma_f32 v25, s56, v96, v25
	v_fma_f32 v24, s57, v81, v24
	v_fma_f32 v25, s57, v97, v25
	v_fma_f32 v24, s58, v82, v24
	v_fma_f32 v25, s58, v98, v25
	v_fma_f32 v24, s59, v83, v24
	v_fma_f32 v25, s59, v99, v25
	v_fma_f32 v24, s60, v84, v24
	v_fma_f32 v25, s60, v100, v25
	v_fma_f32 v24, s61, v85, v24
	v_fma_f32 v25, s61, v101, v25
	v_fma_f32 v24, s62, v86, v24
	v_fma_f32 v25, s62, v102, v25
	v_fma_f32 v24, s63, v87, v24
	v_fma_f32 v25, s63, v103, v25
	s_mov_b32 s10, s6
	v_readlane_b32 s0, v246, 49
	v_readlane_b32 s1, v246, 50
	s_ashr_i32 s30, s24, 5
	s_lshl_b32 s31, s30, 12
	v_lshl_add_u64 v[4:5], s[0:1], 0, v[2:3]
	global_load_dword v28, v[4:5], off
	v_lshl_add_u64 v[4:5], s[26:27], 0, v[2:3]
	v_add_co_u32_e32 v6, vcc, 0x1000, v4
	v_readlane_b32 s0, v246, 43
	s_nop 0
	v_addc_co_u32_e32 v7, vcc, 0, v5, vcc
	global_load_dword v52, v[4:5], off
	global_load_dword v53, v[4:5], off offset:2048
	global_load_dword v54, v[6:7], off
	global_load_dword v50, v[6:7], off offset:2048
	v_readlane_b32 s1, v246, 44
	s_nop 3
	v_lshl_add_u64 v[4:5], s[0:1], 0, v[2:3]
	global_load_dword v51, v[4:5], off
	v_readlane_b32 s0, v246, 36
	v_readlane_b32 s1, v246, 37
	s_mul_i32 s6, s31, 0x1800
	s_lshl_b32 s7, s10, 7
	s_add_u32 s50, s0, s6
	s_addc_u32 s51, s1, 0
	s_add_i32 s7, s7, 0xffffcc00
	s_ashr_i32 s8, s7, 31
	s_add_u32 s48, s50, s7
	s_addc_u32 s49, s51, s8
	v_readlane_b32 s0, v250, 10
	v_readlane_b32 s1, v250, 11
	s_lshl_b32 s6, s31, 11
	s_nop 1
	s_add_u32 s52, s0, s6
	s_addc_u32 s53, s1, 0
	v_cmp_gt_u32_e64 s[54:55], 24, v20
	s_mov_b32 s56, 0xffff0000
	s_mov_b32 s57, -1
	s_mov_b32 s58, 0
	s_mov_b32 s59, -1
	s_mov_b32 s60, 0
	s_mov_b32 s61, 0xffff0000
	v_lshrrev_b32_e32 v22, 6, v20
	s_nop 0
	v_readfirstlane_b32 s63, v22
	v_and_b32_e32 v35, 7, v20
	v_lshrrev_b32_e32 v36, 3, v20
	v_lshlrev_b32_e32 v35, 4, v35
	v_mul_u32_u24_e32 v56, 0x90, v36
	v_add_u32_e32 v56, v56, v35
	v_mul_u32_u24_e32 v57, 0x1800, v36
	v_add_u32_e32 v57, v57, v35
	v_add_u32_e32 v58, 0x60000, v57
	v_add_u32_e32 v59, 0xc0000, v57
	v_add_u32_e32 v60, 0x120000, v57
	v_add_u32_e32 v37, 0x100, v36
	v_mov_b32_e32 v38, 0x102
	v_cndmask_b32_e64 v37, v38, v37, s[54:55]
	v_mul_u32_u24_e32 v61, 0x1800, v37
	v_add_u32_e32 v61, v61, v35
	v_max_u32_e32 v37, 3, v36
	v_mul_u32_u24_e32 v62, 0x1800, v37
	v_add_u32_e32 v62, v62, v35
	v_lshrrev_b32_e32 v39, 4, v20
	v_and_b32_e32 v40, 3, v39
	v_lshlrev_b32_e32 v41, 5, v22
	v_add_u32_e32 v42, v41, v34
	v_mul_u32_u24_e32 v63, 0x90, v42
	v_lshl_add_u32 v63, v40, 4, v63
	v_lshl_add_u32 v42, v40, 2, v41
	v_mul_u32_u24_e32 v64, 0x84, v42
	v_lshl_add_u32 v64, v34, 2, v64
	v_add_u32_e32 v64, 0xda40, v64
	v_add_u32_e32 v65, 0x840, v64
	v_mul_u32_u24_e32 v66, 0x420, v39
	v_lshl_add_u32 v66, v34, 2, v66
	v_add_u32_e32 v66, 0xda40, v66
	v_mul_u32_u24_e32 v67, 0x480, v39
	v_lshl_add_u32 v67, v21, 1, v67
	v_lshlrev_b32_e32 v68, 3, v20
	v_add_u32_e32 v68, 0x15e40, v68
	v_lshlrev_b32_e32 v69, 3, v34
	v_add_u32_e32 v69, 0x15e40, v69
	v_mul_u32_u24_e32 v43, 0xc000, v39
	v_lshl_add_u32 v43, v26, 1, v43
	v_add_u32_e32 v70, 0x1000, v43
	v_add_u32_e32 v71, 0x1800, v70
	v_add_u32_e32 v72, 0x3000, v70
	v_add_u32_e32 v73, 0x4800, v70
	v_add_u32_e32 v74, 0x6000, v70
	v_add_u32_e32 v75, 0x7800, v70
	v_add_u32_e32 v76, 0x9000, v70
	v_add_u32_e32 v77, 0xa800, v70
	v_lshlrev_b32_e32 v43, 14, v39
	v_lshl_add_u32 v43, v26, 1, v43
	v_add_u32_e32 v78, 0x400, v43
	v_add_u32_e32 v79, 0x800, v78
	v_add_u32_e32 v80, 0x1000, v78
	v_add_u32_e32 v81, 0x1800, v78
	v_add_u32_e32 v82, 0x2000, v78
	v_add_u32_e32 v83, 0x2800, v78
	v_add_u32_e32 v84, 0x3000, v78
	v_add_u32_e32 v85, 0x3800, v78
	v_mul_u32_u24_e32 v44, 0x90, v34
	v_lshl_add_u32 v44, v40, 4, v44
	global_load_dwordx4 v[0:3], v62, s[48:49]
	global_load_dwordx4 v[4:7], v58, s[48:49]
	global_load_dwordx4 v[8:11], v59, s[48:49]
	global_load_dwordx4 v[12:15], v60, s[48:49]
	global_load_dwordx4 v[16:19], v61, s[48:49]
	s_waitcnt lgkmcnt(0)
	s_barrier
	ds_read_b128 v[140:143], v44 offset:37440
	ds_read_b128 v[144:147], v44 offset:37504
	ds_read_b128 v[148:151], v44 offset:39744
	ds_read_b128 v[152:155], v44 offset:39808
	ds_read_b128 v[156:159], v44 offset:42048
	ds_read_b128 v[160:163], v44 offset:42112
	ds_read_b128 v[164:167], v44 offset:44352
	ds_read_b128 v[180:183], v44 offset:44416
	s_waitcnt lgkmcnt(0)
	ds_read_b128 v[184:187], v44 offset:46656
	ds_read_b128 v[188:191], v44 offset:46720
	ds_read_b128 v[192:195], v44 offset:48960
	ds_read_b128 v[196:199], v44 offset:49024
	ds_read_b128 v[200:203], v44 offset:51264
	ds_read_b128 v[204:207], v44 offset:51328
	ds_read_b128 v[208:211], v44 offset:53568
	ds_read_b128 v[212:215], v44 offset:53632
	s_waitcnt vmcnt(5) lgkmcnt(0)
	v_mul_f32_e32 v110, 0xbfb8aa3b, v28
	v_rndne_f32_e32 v111, v110
	s_mov_b32 s6, 0xbfb8aa3b
	v_sub_f32_e32 v112, v110, v111
	v_fma_f32 v110, v28, s6, -v110
	v_fmac_f32_e32 v110, 0xb2a5705f, v28
	v_add_f32_e32 v110, v112, v110
	v_exp_f32_e32 v110, v110
	v_cvt_i32_f32_e32 v111, v111
	s_mov_b32 s6, 0x42ce8ed0
	v_cmp_nlt_f32_e64 s[6:7], s6, v28
	s_mov_b32 s4, 0x7f800000
	v_ldexp_f32 v110, v110, v111
	v_cndmask_b32_e64 v110, 0, v110, s[6:7]
	s_mov_b32 s6, 0xc2b17218
	v_cmp_ngt_f32_e64 s[6:7], s6, v28
	s_nop 1
	v_cndmask_b32_e64 v112, v226, v110, s[6:7]
	v_add_f32_e32 v113, 1.0, v112
	v_add_f32_e32 v110, -1.0, v113
	v_sub_f32_e32 v111, v110, v113
	v_add_f32_e32 v111, 1.0, v111
	v_sub_f32_e32 v110, v112, v110
	v_add_f32_e32 v114, v110, v111
	v_frexp_mant_f32_e32 v110, v113
	s_mov_b32 s6, 0x3f2aaaab
	v_cmp_gt_f32_e64 s[6:7], s6, v110
	v_cvt_f64_f32_e32 v[110:111], v113
	v_frexp_exp_i32_f64_e32 v110, v[110:111]
	v_subbrev_co_u32_e64 v110, s[6:7], 0, v110, s[6:7]
	v_sub_u32_e32 v111, 0, v110
	v_ldexp_f32 v113, v113, v111
	v_ldexp_f32 v111, v114, v111
	v_add_f32_e32 v114, -1.0, v113
	v_add_f32_e32 v115, 1.0, v114
	v_sub_f32_e32 v115, v113, v115
	v_add_f32_e32 v115, v111, v115
	v_add_f32_e32 v116, v114, v115
	v_sub_f32_e32 v114, v114, v116
	v_add_f32_e32 v114, v115, v114
	v_add_f32_e32 v115, 1.0, v113
	v_add_f32_e32 v117, -1.0, v115
	v_sub_f32_e32 v113, v113, v117
	v_add_f32_e32 v111, v111, v113
	v_add_f32_e32 v113, v115, v111
	v_sub_f32_e32 v115, v115, v113
	v_add_f32_e32 v111, v111, v115
	v_rcp_f32_e32 v115, v113
	v_cvt_f32_i32_e32 v110, v110
	s_mov_b32 s6, 0x3f317218
	v_mul_f32_e32 v117, v116, v115
	v_mul_f32_e32 v118, v113, v117
	v_fma_f32 v119, v117, v113, -v118
	v_fmac_f32_e32 v119, v117, v111
	v_add_f32_e32 v120, v118, v119
	v_sub_f32_e32 v121, v116, v120
	v_sub_f32_e32 v116, v116, v121
	v_sub_f32_e32 v118, v120, v118
	v_sub_f32_e32 v116, v116, v120
	v_add_f32_e32 v114, v114, v116
	v_sub_f32_e32 v116, v118, v119
	v_add_f32_e32 v114, v116, v114
	v_add_f32_e32 v116, v121, v114
	v_mul_f32_e32 v118, v115, v116
	v_mul_f32_e32 v119, v113, v118
	v_fma_f32 v113, v118, v113, -v119
	v_fmac_f32_e32 v113, v118, v111
	v_sub_f32_e32 v111, v121, v116
	v_add_f32_e32 v111, v114, v111
	v_add_f32_e32 v114, v119, v113
	v_sub_f32_e32 v120, v116, v114
	v_sub_f32_e32 v116, v116, v120
	v_sub_f32_e32 v119, v114, v119
	v_sub_f32_e32 v114, v116, v114
	v_add_f32_e32 v111, v111, v114
	v_sub_f32_e32 v113, v119, v113
	v_add_f32_e32 v111, v113, v111
	v_add_f32_e32 v113, v117, v118
	v_add_f32_e32 v111, v120, v111
	v_sub_f32_e32 v114, v113, v117
	v_mul_f32_e32 v111, v115, v111
	v_sub_f32_e32 v114, v118, v114
	v_add_f32_e32 v111, v114, v111
	v_mul_f32_e32 v117, 0x3f317218, v110
	v_add_f32_e32 v114, v113, v111
	v_fma_f32 v118, v110, s6, -v117
	v_mul_f32_e32 v115, v114, v114
	v_fmac_f32_e32 v118, 0xb102e308, v110
	v_sub_f32_e32 v110, v114, v113
	v_fmamk_f32 v116, v115, 0x3e9b6dac, v219
	v_sub_f32_e32 v110, v111, v110
	v_add_f32_e32 v111, v117, v118
	v_fmaak_f32 v116, v115, v116, 0x3f2aaada
	v_sub_f32_e32 v113, v111, v117
	v_ldexp_f32 v117, v114, 1
	v_mul_f32_e32 v114, v114, v115
	v_mul_f32_e32 v114, v114, v116
	v_add_f32_e32 v115, v117, v114
	v_sub_f32_e32 v116, v115, v117
	v_ldexp_f32 v110, v110, 1
	v_sub_f32_e32 v114, v114, v116
	v_add_f32_e32 v110, v110, v114
	v_add_f32_e32 v114, v115, v110
	v_sub_f32_e32 v115, v114, v115
	v_sub_f32_e32 v110, v110, v115
	v_add_f32_e32 v115, v111, v114
	v_sub_f32_e32 v116, v115, v111
	v_sub_f32_e32 v117, v115, v116
	v_sub_f32_e32 v113, v118, v113
	v_sub_f32_e32 v111, v111, v117
	v_sub_f32_e32 v114, v114, v116
	v_add_f32_e32 v111, v114, v111
	v_add_f32_e32 v114, v113, v110
	v_sub_f32_e32 v116, v114, v113
	v_sub_f32_e32 v117, v114, v116
	v_sub_f32_e32 v113, v113, v117
	v_sub_f32_e32 v110, v110, v116
	v_add_f32_e32 v111, v114, v111
	v_add_f32_e32 v110, v110, v113
	v_add_f32_e32 v113, v115, v111
	v_sub_f32_e32 v114, v113, v115
	v_sub_f32_e32 v111, v111, v114
	v_add_f32_e32 v110, v110, v111
	v_add_f32_e32 v110, v113, v110
	v_cmp_neq_f32_e64 s[6:7], s4, v112
	s_nop 1
	v_cndmask_b32_e64 v110, v226, v110, s[6:7]
	s_mov_b32 s6, 0x33800000
	v_cmp_lt_f32_e64 s[6:7], |v112|, s6
	s_nop 1
	v_cndmask_b32_e64 v110, v110, v112, s[6:7]
	v_mul_f32_e32 v55, 0xc1000000, v110
	v_mov_b32_e32 v23, 0
	s_mov_b32 s62, 0
.Lrg_tile:
	s_cmp_eq_u32 s62, 0
	s_cbranch_scc1 .Lrg_first
	s_waitcnt vmcnt(8)
	s_branch .Lrg_stage
.Lrg_first:
	s_waitcnt vmcnt(0)
	v_cndmask_b32_e64 v0, v0, 0, s[54:55]
	v_cndmask_b32_e64 v1, v1, 0, s[54:55]
	v_cndmask_b32_e64 v2, v2, 0, s[54:55]
	v_cndmask_b32_e64 v3, v3, 0, s[54:55]
.Lrg_stage:
	ds_write_b128 v56, v[0:3]
	ds_write_b128 v56, v[4:7] offset:9216
	ds_write_b128 v56, v[8:11] offset:18432
	ds_write_b128 v56, v[12:15] offset:27648
	s_mov_b64 exec, s[54:55]
	ds_write_b128 v56, v[16:19] offset:36864
	s_mov_b64 exec, -1
	global_load_ushort v86, v70, s[50:51]
	global_load_ushort v87, v71, s[50:51]
	global_load_ushort v88, v72, s[50:51]
	global_load_ushort v89, v73, s[50:51]
	global_load_ushort v90, v74, s[50:51]
	global_load_ushort v91, v75, s[50:51]
	global_load_ushort v92, v76, s[50:51]
	global_load_ushort v93, v77, s[50:51]
	s_waitcnt lgkmcnt(0)
	s_cmp_eq_u32 s62, 15
	s_cbranch_scc1 .Lrg_nopref
	s_add_u32 s48, s48, 0x180000
	s_addc_u32 s49, s49, 0
	global_load_dwordx4 v[0:3], v57, s[48:49]
	global_load_dwordx4 v[4:7], v58, s[48:49]
	global_load_dwordx4 v[8:11], v59, s[48:49]
	global_load_dwordx4 v[12:15], v60, s[48:49]
	global_load_dwordx4 v[16:19], v61, s[48:49]
.Lrg_nopref:
	s_barrier
	ds_read_b128 v[108:111], v63 offset:0
	ds_read_b128 v[112:115], v63 offset:64
	ds_read_b128 v[116:119], v63 offset:144
	ds_read_b128 v[120:123], v63 offset:208
	ds_read_b128 v[124:127], v63 offset:288
	ds_read_b128 v[128:131], v63 offset:352
	ds_read_b128 v[132:135], v63 offset:432
	ds_read_b128 v[136:139], v63 offset:496
	s_waitcnt lgkmcnt(6)
	v_mfma_f32_16x16x32_bf16 v[228:231], v[108:111], v[140:143], 0
	v_mfma_f32_16x16x32_bf16 v[228:231], v[112:115], v[144:147], v[228:231]
	v_mfma_f32_16x16x32_bf16 v[232:235], v[108:111], v[148:151], 0
	v_mfma_f32_16x16x32_bf16 v[232:235], v[112:115], v[152:155], v[232:235]
	ds_read_b128 v[108:111], v63 offset:2304
	ds_read_b128 v[112:115], v63 offset:2368
	s_waitcnt lgkmcnt(6)
	v_mfma_f32_16x16x32_bf16 v[228:231], v[116:119], v[156:159], v[228:231]
	v_mfma_f32_16x16x32_bf16 v[228:231], v[120:123], v[160:163], v[228:231]
	v_mfma_f32_16x16x32_bf16 v[232:235], v[116:119], v[164:167], v[232:235]
	v_mfma_f32_16x16x32_bf16 v[232:235], v[120:123], v[180:183], v[232:235]
	ds_read_b128 v[116:119], v63 offset:2448
	ds_read_b128 v[120:123], v63 offset:2512
	s_waitcnt lgkmcnt(6)
	v_mfma_f32_16x16x32_bf16 v[228:231], v[124:127], v[184:187], v[228:231]
	v_mfma_f32_16x16x32_bf16 v[228:231], v[128:131], v[188:191], v[228:231]
	v_mfma_f32_16x16x32_bf16 v[232:235], v[124:127], v[192:195], v[232:235]
	v_mfma_f32_16x16x32_bf16 v[232:235], v[128:131], v[196:199], v[232:235]
	ds_read_b128 v[124:127], v63 offset:2592
	ds_read_b128 v[128:131], v63 offset:2656
	s_waitcnt lgkmcnt(6)
	v_mfma_f32_16x16x32_bf16 v[228:231], v[132:135], v[200:203], v[228:231]
	v_mfma_f32_16x16x32_bf16 v[228:231], v[136:139], v[204:207], v[228:231]
	v_mfma_f32_16x16x32_bf16 v[232:235], v[132:135], v[208:211], v[232:235]
	v_mfma_f32_16x16x32_bf16 v[232:235], v[136:139], v[212:215], v[232:235]
	ds_read_b128 v[132:135], v63 offset:2736
	ds_read_b128 v[136:139], v63 offset:2800
	s_waitcnt lgkmcnt(6)
	v_mfma_f32_16x16x32_bf16 v[236:239], v[108:111], v[140:143], 0
	v_mfma_f32_16x16x32_bf16 v[236:239], v[112:115], v[144:147], v[236:239]
	v_mfma_f32_16x16x32_bf16 v[240:243], v[108:111], v[148:151], 0
	v_mfma_f32_16x16x32_bf16 v[240:243], v[112:115], v[152:155], v[240:243]
	s_waitcnt lgkmcnt(4)
	v_mfma_f32_16x16x32_bf16 v[236:239], v[116:119], v[156:159], v[236:239]
	v_mfma_f32_16x16x32_bf16 v[236:239], v[120:123], v[160:163], v[236:239]
	v_mfma_f32_16x16x32_bf16 v[240:243], v[116:119], v[164:167], v[240:243]
	v_mfma_f32_16x16x32_bf16 v[240:243], v[120:123], v[180:183], v[240:243]
	s_waitcnt lgkmcnt(2)
	v_mfma_f32_16x16x32_bf16 v[236:239], v[124:127], v[184:187], v[236:239]
	v_mfma_f32_16x16x32_bf16 v[236:239], v[128:131], v[188:191], v[236:239]
	v_mfma_f32_16x16x32_bf16 v[240:243], v[124:127], v[192:195], v[240:243]
	v_mfma_f32_16x16x32_bf16 v[240:243], v[128:131], v[196:199], v[240:243]
	s_waitcnt lgkmcnt(0)
	v_mfma_f32_16x16x32_bf16 v[236:239], v[132:135], v[200:203], v[236:239]
	v_mfma_f32_16x16x32_bf16 v[236:239], v[136:139], v[204:207], v[236:239]
	v_mfma_f32_16x16x32_bf16 v[240:243], v[132:135], v[208:211], v[240:243]
	v_mfma_f32_16x16x32_bf16 v[240:243], v[136:139], v[212:215], v[240:243]
	s_nop 7
	s_nop 1
	ds_write2_b32 v64, v228, v229 offset0:0 offset1:33
	ds_write2_b32 v64, v230, v231 offset0:66 offset1:99
	ds_write2_b32 v64, v232, v233 offset0:16 offset1:49
	ds_write2_b32 v64, v234, v235 offset0:82 offset1:115
	ds_write2_b32 v65, v236, v237 offset0:0 offset1:33
	ds_write2_b32 v65, v238, v239 offset0:66 offset1:99
	ds_write2_b32 v65, v240, v241 offset0:16 offset1:49
	ds_write2_b32 v65, v242, v243 offset0:82 offset1:115
	s_waitcnt lgkmcnt(0)
	s_barrier
	ds_read2_b32 v[110:111], v66 offset0:0 offset1:16
	ds_read2_b32 v[112:113], v66 offset0:33 offset1:49
	ds_read2_b32 v[114:115], v66 offset0:66 offset1:82
	ds_read2_b32 v[116:117], v66 offset0:99 offset1:115
	ds_read2_b32 v[118:119], v66 offset0:132 offset1:148
	ds_read2_b32 v[120:121], v66 offset0:165 offset1:181
	ds_read2_b32 v[122:123], v66 offset0:198 offset1:214
	ds_read2_b32 v[124:125], v66 offset0:231 offset1:247
	ds_read_u16 v126, v67 offset:0
	ds_read_u16 v127, v67 offset:144
	ds_read_u16 v128, v67 offset:288
	ds_read_u16 v129, v67 offset:432
	ds_read_u16 v130, v67 offset:576
	ds_read_u16 v131, v67 offset:720
	ds_read_u16 v132, v67 offset:864
	s_waitcnt lgkmcnt(7)
	v_add_f32_e32 v110, v24, v110
	v_add_f32_e32 v112, v24, v112
	v_add_f32_e32 v114, v24, v114
	v_add_f32_e32 v116, v24, v116
	v_add_f32_e32 v118, v24, v118
	v_add_f32_e32 v120, v24, v120
	v_add_f32_e32 v122, v24, v122
	v_add_f32_e32 v124, v24, v124
	v_add_f32_e32 v111, v25, v111
	v_add_f32_e32 v113, v25, v113
	v_add_f32_e32 v115, v25, v115
	v_add_f32_e32 v117, v25, v117
	v_add_f32_e32 v119, v25, v119
	v_add_f32_e32 v121, v25, v121
	v_add_f32_e32 v123, v25, v123
	v_add_f32_e32 v125, v25, v125
	ds_read_u16 v133, v67 offset:1008
	ds_read_u16 v134, v67 offset:1152
	ds_read_u16 v135, v67 offset:1296
	ds_read_u16 v136, v67 offset:1440
	v_mul_f32_e32 v110, 0xbfb8aa3b, v110
	v_mul_f32_e32 v112, 0xbfb8aa3b, v112
	v_mul_f32_e32 v114, 0xbfb8aa3b, v114
	v_mul_f32_e32 v116, 0xbfb8aa3b, v116
	v_mul_f32_e32 v118, 0xbfb8aa3b, v118
	v_mul_f32_e32 v120, 0xbfb8aa3b, v120
	v_mul_f32_e32 v122, 0xbfb8aa3b, v122
	v_mul_f32_e32 v124, 0xbfb8aa3b, v124
	v_mul_f32_e32 v111, 0xbfb8aa3b, v111
	v_mul_f32_e32 v113, 0xbfb8aa3b, v113
	v_mul_f32_e32 v115, 0xbfb8aa3b, v115
	v_mul_f32_e32 v117, 0xbfb8aa3b, v117
	v_mul_f32_e32 v119, 0xbfb8aa3b, v119
	v_mul_f32_e32 v121, 0xbfb8aa3b, v121
	v_mul_f32_e32 v123, 0xbfb8aa3b, v123
	v_mul_f32_e32 v125, 0xbfb8aa3b, v125
	v_exp_f32_e32 v110, v110
	v_exp_f32_e32 v112, v112
	v_exp_f32_e32 v114, v114
	v_exp_f32_e32 v116, v116
	v_exp_f32_e32 v118, v118
	v_exp_f32_e32 v120, v120
	v_exp_f32_e32 v122, v122
	v_exp_f32_e32 v124, v124
	v_exp_f32_e32 v111, v111
	v_exp_f32_e32 v113, v113
	v_exp_f32_e32 v115, v115
	v_exp_f32_e32 v117, v117
	v_exp_f32_e32 v119, v119
	v_exp_f32_e32 v121, v121
	v_exp_f32_e32 v123, v123
	v_exp_f32_e32 v125, v125
	v_add_f32_e32 v110, 1.0, v110
	v_add_f32_e32 v112, 1.0, v112
	v_add_f32_e32 v114, 1.0, v114
	v_add_f32_e32 v116, 1.0, v116
	v_add_f32_e32 v118, 1.0, v118
	v_add_f32_e32 v120, 1.0, v120
	v_add_f32_e32 v122, 1.0, v122
	v_add_f32_e32 v124, 1.0, v124
	v_add_f32_e32 v111, 1.0, v111
	v_add_f32_e32 v113, 1.0, v113
	v_add_f32_e32 v115, 1.0, v115
	v_add_f32_e32 v117, 1.0, v117
	v_add_f32_e32 v119, 1.0, v119
	v_add_f32_e32 v121, 1.0, v121
	v_add_f32_e32 v123, 1.0, v123
	v_add_f32_e32 v125, 1.0, v125
	v_rcp_f32_e32 v110, v110
	v_rcp_f32_e32 v112, v112
	v_rcp_f32_e32 v114, v114
	v_rcp_f32_e32 v116, v116
	v_rcp_f32_e32 v118, v118
	v_rcp_f32_e32 v120, v120
	v_rcp_f32_e32 v122, v122
	v_rcp_f32_e32 v124, v124
	v_rcp_f32_e32 v111, v111
	v_rcp_f32_e32 v113, v113
	v_rcp_f32_e32 v115, v115
	v_rcp_f32_e32 v117, v117
	v_rcp_f32_e32 v119, v119
	v_rcp_f32_e32 v121, v121
	v_rcp_f32_e32 v123, v123
	v_rcp_f32_e32 v125, v125
	v_mul_f32_e32 v110, v55, v110
	v_mul_f32_e32 v112, v55, v112
	v_mul_f32_e32 v114, v55, v114
	v_mul_f32_e32 v116, v55, v116
	v_mul_f32_e32 v118, v55, v118
	v_mul_f32_e32 v120, v55, v120
	v_mul_f32_e32 v122, v55, v122
	v_mul_f32_e32 v124, v55, v124
	v_mul_f32_e32 v236, 0x3fb8aa3b, v110
	v_mul_f32_e32 v237, 0x3fb8aa3b, v112
	v_mul_f32_e32 v238, 0x3fb8aa3b, v114
	v_mul_f32_e32 v239, 0x3fb8aa3b, v116
	v_mul_f32_e32 v240, 0x3fb8aa3b, v118
	v_mul_f32_e32 v241, 0x3fb8aa3b, v120
	v_mul_f32_e32 v242, 0x3fb8aa3b, v122
	v_mul_f32_e32 v243, 0x3fb8aa3b, v124
	v_exp_f32_e32 v94, v236
	v_exp_f32_e32 v95, v237
	v_exp_f32_e32 v96, v238
	v_exp_f32_e32 v97, v239
	v_exp_f32_e32 v98, v240
	v_exp_f32_e32 v99, v241
	v_exp_f32_e32 v100, v242
	v_exp_f32_e32 v101, v243
	v_add_f32_e32 v110, v110, v110
	v_add_f32_e32 v112, v112, v112
	v_add_f32_e32 v114, v114, v114
	v_add_f32_e32 v116, v116, v116
	v_add_f32_e32 v118, v118, v118
	v_add_f32_e32 v120, v120, v120
	v_add_f32_e32 v122, v122, v122
	v_add_f32_e32 v124, v124, v124
	v_mul_f32_e32 v236, 0x3e2aaaab, v110
	v_mul_f32_e32 v237, 0x3e2aaaab, v112
	v_mul_f32_e32 v238, 0x3e2aaaab, v114
	v_mul_f32_e32 v239, 0x3e2aaaab, v116
	v_mul_f32_e32 v240, 0x3e2aaaab, v118
	v_mul_f32_e32 v241, 0x3e2aaaab, v120
	v_mul_f32_e32 v242, 0x3e2aaaab, v122
	v_mul_f32_e32 v243, 0x3e2aaaab, v124
	v_mul_f32_e32 v35, v110, v170
	v_mul_f32_e32 v36, v112, v170
	v_mul_f32_e32 v37, v114, v170
	v_mul_f32_e32 v38, v116, v170
	v_mul_f32_e32 v39, v118, v170
	v_mul_f32_e32 v40, v120, v170
	v_mul_f32_e32 v41, v122, v170
	v_mul_f32_e32 v42, v124, v170
	v_fma_f32 v228, -v94, v94, 1.0
	v_fma_f32 v229, -v95, v95, 1.0
	v_fma_f32 v230, -v96, v96, 1.0
	v_fma_f32 v231, -v97, v97, 1.0
	v_fma_f32 v232, -v98, v98, 1.0
	v_fma_f32 v233, -v99, v99, 1.0
	v_fma_f32 v234, -v100, v100, 1.0
	v_fma_f32 v235, -v101, v101, 1.0
	v_mul_f32_e32 v236, v110, v236
	v_mul_f32_e32 v237, v112, v237
	v_mul_f32_e32 v238, v114, v238
	v_mul_f32_e32 v239, v116, v239
	v_mul_f32_e32 v240, v118, v240
	v_mul_f32_e32 v241, v120, v241
	v_mul_f32_e32 v242, v122, v242
	v_mul_f32_e32 v243, v124, v243
	v_mul_f32_e32 v35, v110, v35
	v_mul_f32_e32 v36, v112, v36
	v_mul_f32_e32 v37, v114, v37
	v_mul_f32_e32 v38, v116, v38
	v_mul_f32_e32 v39, v118, v39
	v_mul_f32_e32 v40, v120, v40
	v_mul_f32_e32 v41, v122, v41
	v_mul_f32_e32 v42, v124, v42
	v_mul_f32_e32 v236, v110, v236
	v_mul_f32_e32 v237, v112, v237
	v_mul_f32_e32 v238, v114, v238
	v_mul_f32_e32 v239, v116, v239
	v_mul_f32_e32 v240, v118, v240
	v_mul_f32_e32 v241, v120, v241
	v_mul_f32_e32 v242, v122, v242
	v_mul_f32_e32 v243, v124, v243
	v_add_f32_e32 v35, v110, v35
	v_add_f32_e32 v36, v112, v36
	v_add_f32_e32 v37, v114, v37
	v_add_f32_e32 v38, v116, v38
	v_add_f32_e32 v39, v118, v39
	v_add_f32_e32 v40, v120, v40
	v_add_f32_e32 v41, v122, v41
	v_add_f32_e32 v42, v124, v42
	v_cmp_nlt_f32_e64 s[64:65], s33, v110
	v_cmp_nlt_f32_e64 s[66:67], s33, v112
	v_cmp_nlt_f32_e64 s[68:69], s33, v114
	v_cmp_nlt_f32_e64 s[70:71], s33, v116
	v_cmp_nlt_f32_e64 s[72:73], s33, v118
	v_cmp_nlt_f32_e64 s[74:75], s33, v120
	v_cmp_nlt_f32_e64 s[76:77], s33, v122
	v_cmp_nlt_f32_e64 s[78:79], s33, v124
	v_add_f32_e32 v35, v35, v236
	v_add_f32_e32 v36, v36, v237
	v_add_f32_e32 v37, v37, v238
	v_add_f32_e32 v38, v38, v239
	v_add_f32_e32 v39, v39, v240
	v_add_f32_e32 v40, v40, v241
	v_add_f32_e32 v41, v41, v242
	v_add_f32_e32 v42, v42, v243
	v_xor_b32_e32 v35, 0x80000000, v35
	v_xor_b32_e32 v36, 0x80000000, v36
	v_xor_b32_e32 v37, 0x80000000, v37
	v_xor_b32_e32 v38, 0x80000000, v38
	v_xor_b32_e32 v39, 0x80000000, v39
	v_xor_b32_e32 v40, 0x80000000, v40
	v_xor_b32_e32 v41, 0x80000000, v41
	v_xor_b32_e32 v42, 0x80000000, v42
	v_cndmask_b32_e64 v228, v35, v228, s[64:65]
	v_cndmask_b32_e64 v229, v36, v229, s[66:67]
	v_cndmask_b32_e64 v230, v37, v230, s[68:69]
	v_cndmask_b32_e64 v231, v38, v231, s[70:71]
	v_cndmask_b32_e64 v232, v39, v232, s[72:73]
	v_cndmask_b32_e64 v233, v40, v233, s[74:75]
	v_cndmask_b32_e64 v234, v41, v234, s[76:77]
	v_cndmask_b32_e64 v235, v42, v235, s[78:79]
	v_max_f32_e32 v228, v228, v228
	v_max_f32_e32 v229, v229, v229
	v_max_f32_e32 v230, v230, v230
	v_max_f32_e32 v231, v231, v231
	v_max_f32_e32 v232, v232, v232
	v_max_f32_e32 v233, v233, v233
	v_max_f32_e32 v234, v234, v234
	v_max_f32_e32 v235, v235, v235
	v_max_f32_e32 v228, 0, v228
	v_max_f32_e32 v229, 0, v229
	v_max_f32_e32 v230, 0, v230
	v_max_f32_e32 v231, 0, v231
	v_max_f32_e32 v232, 0, v232
	v_max_f32_e32 v233, 0, v233
	v_max_f32_e32 v234, 0, v234
	v_max_f32_e32 v235, 0, v235
	v_sqrt_f32_e32 v228, v228
	v_sqrt_f32_e32 v229, v229
	v_sqrt_f32_e32 v230, v230
	v_sqrt_f32_e32 v231, v231
	v_sqrt_f32_e32 v232, v232
	v_sqrt_f32_e32 v233, v233
	v_sqrt_f32_e32 v234, v234
	v_sqrt_f32_e32 v235, v235
	s_waitcnt lgkmcnt(0)
	v_lshlrev_b32_e32 v126, 16, v126
	v_lshlrev_b32_e32 v127, 16, v127
	v_lshlrev_b32_e32 v128, 16, v128
	v_lshlrev_b32_e32 v129, 16, v129
	v_lshlrev_b32_e32 v130, 16, v130
	v_lshlrev_b32_e32 v131, 16, v131
	v_lshlrev_b32_e32 v132, 16, v132
	v_lshlrev_b32_e32 v133, 16, v133
	v_lshlrev_b32_e32 v134, 16, v134
	v_lshlrev_b32_e32 v135, 16, v135
	v_lshlrev_b32_e32 v136, 16, v136
	v_fma_f32 v110, v52, v126, v51
	v_fma_f32 v112, v52, v127, v51
	v_fma_f32 v114, v52, v128, v51
	v_fma_f32 v116, v52, v129, v51
	v_fma_f32 v118, v52, v130, v51
	v_fma_f32 v120, v52, v131, v51
	v_fma_f32 v122, v52, v132, v51
	v_fma_f32 v124, v52, v133, v51
	v_fmac_f32_e32 v110, v53, v127
	v_fmac_f32_e32 v112, v53, v128
	v_fmac_f32_e32 v114, v53, v129
	v_fmac_f32_e32 v116, v53, v130
	v_fmac_f32_e32 v118, v53, v131
	v_fmac_f32_e32 v120, v53, v132
	v_fmac_f32_e32 v122, v53, v133
	v_fmac_f32_e32 v124, v53, v134
	v_fmac_f32_e32 v110, v54, v128
	v_fmac_f32_e32 v112, v54, v129
	v_fmac_f32_e32 v114, v54, v130
	v_fmac_f32_e32 v116, v54, v131
	v_fmac_f32_e32 v118, v54, v132
	v_fmac_f32_e32 v120, v54, v133
	v_fmac_f32_e32 v122, v54, v134
	v_fmac_f32_e32 v124, v54, v135
	v_fmac_f32_e32 v110, v50, v129
	v_fmac_f32_e32 v112, v50, v130
	v_fmac_f32_e32 v114, v50, v131
	v_fmac_f32_e32 v116, v50, v132
	v_fmac_f32_e32 v118, v50, v133
	v_fmac_f32_e32 v120, v50, v134
	v_fmac_f32_e32 v122, v50, v135
	v_fmac_f32_e32 v124, v50, v136
	v_mul_f32_e32 v111, v111, v110
	v_mul_f32_e32 v113, v113, v112
	v_mul_f32_e32 v115, v115, v114
	v_mul_f32_e32 v117, v117, v116
	v_mul_f32_e32 v119, v119, v118
	v_mul_f32_e32 v121, v121, v120
	v_mul_f32_e32 v123, v123, v122
	v_mul_f32_e32 v125, v125, v124
	v_mul_f32_e32 v102, v228, v111
	v_mul_f32_e32 v103, v229, v113
	v_mul_f32_e32 v104, v230, v115
	v_mul_f32_e32 v105, v231, v117
	v_mul_f32_e32 v106, v232, v119
	v_mul_f32_e32 v107, v233, v121
	v_mul_f32_e32 v108, v234, v123
	v_mul_f32_e32 v109, v235, v125
	v_fma_f32 v44, 0, v94, v102
	v_mul_f32_e32 v45, v94, v95
	v_fma_f32 v44, v44, v95, v103
	v_fma_f32 v44, v44, v96, v104
	v_mul_f32_e32 v45, v45, v96
	v_fma_f32 v44, v44, v97, v105
	v_mul_f32_e32 v45, v45, v97
	v_fma_f32 v44, v44, v98, v106
	v_mul_f32_e32 v45, v45, v98
	v_fma_f32 v44, v44, v99, v107
	v_mul_f32_e32 v45, v45, v99
	v_fma_f32 v44, v44, v100, v108
	v_mul_f32_e32 v45, v45, v100
	v_fma_f32 v44, v44, v101, v109
	v_mul_f32_e32 v45, v45, v101
	v_mov_b32_e32 v46, v45
	v_mov_b32_e32 v47, v44
	ds_write_b64 v68, v[46:47]
	s_waitcnt lgkmcnt(0)
	s_barrier
	v_add_u32_e32 v48, 0x800, v69
	ds_read2_b64 v[112:115], v69 offset0:0 offset1:16
	ds_read2_b64 v[116:119], v69 offset0:32 offset1:48
	ds_read2_b64 v[120:123], v69 offset0:64 offset1:80
	ds_read2_b64 v[124:127], v69 offset0:96 offset1:112
	ds_read2_b64 v[128:131], v69 offset0:128 offset1:144
	ds_read2_b64 v[132:135], v69 offset0:160 offset1:176
	ds_read2_b64 v[136:139], v69 offset0:192 offset1:208
	ds_read2_b64 v[228:231], v69 offset0:224 offset1:240
	v_mov_b32_e32 v22, v23
	v_mov_b32_e32 v49, 0
	s_waitcnt lgkmcnt(4)
	s_cmp_eq_u32 s63, 0
	s_cbranch_scc1 .Lrg_sel0
	v_fma_f32 v22, v22, v112, v113
	v_fma_f32 v22, v22, v114, v115
	v_fma_f32 v22, v22, v116, v117
	v_fma_f32 v22, v22, v118, v119
	s_branch .Lrg_nxt0
.Lrg_sel0:
	v_mov_b32_e32 v49, v22
	v_fma_f32 v22, v22, v112, v113
	v_cndmask_b32_e64 v49, v49, v22, s[56:57]
	v_fma_f32 v22, v22, v114, v115
	v_cndmask_b32_e64 v49, v49, v22, s[58:59]
	v_fma_f32 v22, v22, v116, v117
	v_cndmask_b32_e64 v49, v49, v22, s[60:61]
	v_fma_f32 v22, v22, v118, v119
.Lrg_nxt0:
	s_cmp_eq_u32 s63, 1
	s_cbranch_scc1 .Lrg_sel1
	v_fma_f32 v22, v22, v120, v121
	v_fma_f32 v22, v22, v122, v123
	v_fma_f32 v22, v22, v124, v125
	v_fma_f32 v22, v22, v126, v127
	s_branch .Lrg_nxt1
.Lrg_sel1:
	v_mov_b32_e32 v49, v22
	v_fma_f32 v22, v22, v120, v121
	v_cndmask_b32_e64 v49, v49, v22, s[56:57]
	v_fma_f32 v22, v22, v122, v123
	v_cndmask_b32_e64 v49, v49, v22, s[58:59]
	v_fma_f32 v22, v22, v124, v125
	v_cndmask_b32_e64 v49, v49, v22, s[60:61]
	v_fma_f32 v22, v22, v126, v127
.Lrg_nxt1:
	ds_read2_b64 v[112:115], v48 offset0:0 offset1:16
	ds_read2_b64 v[116:119], v48 offset0:32 offset1:48
	ds_read2_b64 v[120:123], v48 offset0:64 offset1:80
	ds_read2_b64 v[124:127], v48 offset0:96 offset1:112
	s_waitcnt lgkmcnt(4)
	s_cmp_eq_u32 s63, 2
	s_cbranch_scc1 .Lrg_sel2
	v_fma_f32 v22, v22, v128, v129
	v_fma_f32 v22, v22, v130, v131
	v_fma_f32 v22, v22, v132, v133
	v_fma_f32 v22, v22, v134, v135
	s_branch .Lrg_nxt2
.Lrg_sel2:
	v_mov_b32_e32 v49, v22
	v_fma_f32 v22, v22, v128, v129
	v_cndmask_b32_e64 v49, v49, v22, s[56:57]
	v_fma_f32 v22, v22, v130, v131
	v_cndmask_b32_e64 v49, v49, v22, s[58:59]
	v_fma_f32 v22, v22, v132, v133
	v_cndmask_b32_e64 v49, v49, v22, s[60:61]
	v_fma_f32 v22, v22, v134, v135
.Lrg_nxt2:
	s_cmp_eq_u32 s63, 3
	s_cbranch_scc1 .Lrg_sel3
	v_fma_f32 v22, v22, v136, v137
	v_fma_f32 v22, v22, v138, v139
	v_fma_f32 v22, v22, v228, v229
	v_fma_f32 v22, v22, v230, v231
	s_branch .Lrg_nxt3
.Lrg_sel3:
	v_mov_b32_e32 v49, v22
	v_fma_f32 v22, v22, v136, v137
	v_cndmask_b32_e64 v49, v49, v22, s[56:57]
	v_fma_f32 v22, v22, v138, v139
	v_cndmask_b32_e64 v49, v49, v22, s[58:59]
	v_fma_f32 v22, v22, v228, v229
	v_cndmask_b32_e64 v49, v49, v22, s[60:61]
	v_fma_f32 v22, v22, v230, v231
.Lrg_nxt3:
	ds_read2_b64 v[128:131], v48 offset0:128 offset1:144
	ds_read2_b64 v[132:135], v48 offset0:160 offset1:176
	ds_read2_b64 v[136:139], v48 offset0:192 offset1:208
	ds_read2_b64 v[228:231], v48 offset0:224 offset1:240
	s_waitcnt lgkmcnt(4)
	s_cmp_eq_u32 s63, 4
	s_cbranch_scc1 .Lrg_sel4
	v_fma_f32 v22, v22, v112, v113
	v_fma_f32 v22, v22, v114, v115
	v_fma_f32 v22, v22, v116, v117
	v_fma_f32 v22, v22, v118, v119
	s_branch .Lrg_nxt4

.Lrg_nxt4:
	s_cmp_eq_u32 s63, 5
	s_cbranch_scc1 .Lrg_sel5
	v_fma_f32 v22, v22, v120, v121
	v_fma_f32 v22, v22, v122, v123
	v_fma_f32 v22, v22, v124, v125
	v_fma_f32 v22, v22, v126, v127
	s_branch .Lrg_nxt5

.Lrg_nxt5:
	s_waitcnt lgkmcnt(0)
	s_cmp_eq_u32 s63, 6
	s_cbranch_scc1 .Lrg_sel6
	v_fma_f32 v22, v22, v128, v129
	v_fma_f32 v22, v22, v130, v131
	v_fma_f32 v22, v22, v132, v133
	v_fma_f32 v22, v22, v134, v135
	s_branch .Lrg_nxt6

.Lrg_nxt6:
	s_cmp_eq_u32 s63, 7
	s_cbranch_scc1 .Lrg_sel7
	v_fma_f32 v22, v22, v136, v137
	v_fma_f32 v22, v22, v138, v139
	v_fma_f32 v22, v22, v228, v229
	v_fma_f32 v22, v22, v230, v231
	s_branch .Lrg_nxt7

.Lrg_nxt7:
	v_mov_b32_e32 v23, v22
	v_fmac_f32_e32 v102, v94, v49
	v_fmac_f32_e32 v103, v95, v102
	v_fmac_f32_e32 v104, v96, v103
	v_fmac_f32_e32 v105, v97, v104
	v_fmac_f32_e32 v106, v98, v105
	v_fmac_f32_e32 v107, v99, v106
	v_fmac_f32_e32 v108, v100, v107
	v_fmac_f32_e32 v109, v101, v108
	s_cmp_eq_u32 s62, 15
	s_cbranch_scc1 .Lrg_w0
	s_waitcnt vmcnt(5)
	s_branch .Lrg_gate

.Lrg_gate:
	v_lshlrev_b32_e32 v86, 16, v86
	v_lshlrev_b32_e32 v87, 16, v87
	v_lshlrev_b32_e32 v88, 16, v88
	v_lshlrev_b32_e32 v89, 16, v89
	v_lshlrev_b32_e32 v90, 16, v90
	v_lshlrev_b32_e32 v91, 16, v91
	v_lshlrev_b32_e32 v92, 16, v92
	v_lshlrev_b32_e32 v93, 16, v93
	v_mul_f32_e32 v110, 0x3d372713, v86
	v_mul_f32_e32 v111, 0x3d372713, v87
	v_mul_f32_e32 v112, 0x3d372713, v88
	v_mul_f32_e32 v113, 0x3d372713, v89
	v_mul_f32_e32 v114, 0x3d372713, v90
	v_mul_f32_e32 v115, 0x3d372713, v91
	v_mul_f32_e32 v116, 0x3d372713, v92
	v_mul_f32_e32 v117, 0x3d372713, v93
	v_mul_f32_e32 v110, v110, v86
	v_mul_f32_e32 v111, v111, v87
	v_mul_f32_e32 v112, v112, v88
	v_mul_f32_e32 v113, v113, v89
	v_mul_f32_e32 v114, v114, v90
	v_mul_f32_e32 v115, v115, v91
	v_mul_f32_e32 v116, v116, v92
	v_mul_f32_e32 v117, v117, v93
	v_fma_f32 v110, v110, v86, v86
	v_fma_f32 v111, v111, v87, v87
	v_fma_f32 v112, v112, v88, v88
	v_fma_f32 v113, v113, v89, v89
	v_fma_f32 v114, v114, v90, v90
	v_fma_f32 v115, v115, v91, v91
	v_fma_f32 v116, v116, v92, v92
	v_fma_f32 v117, v117, v93, v93
	v_mul_f32_e32 v110, 0x3f4c422a, v110
	v_mul_f32_e32 v111, 0x3f4c422a, v111
	v_mul_f32_e32 v112, 0x3f4c422a, v112
	v_mul_f32_e32 v113, 0x3f4c422a, v113
	v_mul_f32_e32 v114, 0x3f4c422a, v114
	v_mul_f32_e32 v115, 0x3f4c422a, v115
	v_mul_f32_e32 v116, 0x3f4c422a, v116
	v_mul_f32_e32 v117, 0x3f4c422a, v117
	v_add_f32_e32 v110, v110, v110
	v_add_f32_e32 v111, v111, v111
	v_add_f32_e32 v112, v112, v112
	v_add_f32_e32 v113, v113, v113
	v_add_f32_e32 v114, v114, v114
	v_add_f32_e32 v115, v115, v115
	v_add_f32_e32 v116, v116, v116
	v_add_f32_e32 v117, v117, v117
	v_mul_f32_e32 v110, 0x3fb8aa3b, v110
	v_mul_f32_e32 v111, 0x3fb8aa3b, v111
	v_mul_f32_e32 v112, 0x3fb8aa3b, v112
	v_mul_f32_e32 v113, 0x3fb8aa3b, v113
	v_mul_f32_e32 v114, 0x3fb8aa3b, v114
	v_mul_f32_e32 v115, 0x3fb8aa3b, v115
	v_mul_f32_e32 v116, 0x3fb8aa3b, v116
	v_mul_f32_e32 v117, 0x3fb8aa3b, v117
	v_exp_f32_e32 v110, v110
	v_exp_f32_e32 v111, v111
	v_exp_f32_e32 v112, v112
	v_exp_f32_e32 v113, v113
	v_exp_f32_e32 v114, v114
	v_exp_f32_e32 v115, v115
	v_exp_f32_e32 v116, v116
	v_exp_f32_e32 v117, v117
	v_mul_f32_e32 v86, 0.5, v86
	v_mul_f32_e32 v87, 0.5, v87
	v_mul_f32_e32 v88, 0.5, v88
	v_mul_f32_e32 v89, 0.5, v89
	v_mul_f32_e32 v90, 0.5, v90
	v_mul_f32_e32 v91, 0.5, v91
	v_mul_f32_e32 v92, 0.5, v92
	v_mul_f32_e32 v93, 0.5, v93
	v_add_f32_e32 v110, 1.0, v110
	v_add_f32_e32 v111, 1.0, v111
	v_add_f32_e32 v112, 1.0, v112
	v_add_f32_e32 v113, 1.0, v113
	v_add_f32_e32 v114, 1.0, v114
	v_add_f32_e32 v115, 1.0, v115
	v_add_f32_e32 v116, 1.0, v116
	v_add_f32_e32 v117, 1.0, v117
	v_rcp_f32_e32 v110, v110
	v_rcp_f32_e32 v111, v111
	v_rcp_f32_e32 v112, v112
	v_rcp_f32_e32 v113, v113
	v_rcp_f32_e32 v114, v114
	v_rcp_f32_e32 v115, v115
	v_rcp_f32_e32 v116, v116
	v_rcp_f32_e32 v117, v117
	v_fma_f32 v110, v110, -2.0, 1.0
	v_fma_f32 v111, v111, -2.0, 1.0
	v_fma_f32 v112, v112, -2.0, 1.0
	v_fma_f32 v113, v113, -2.0, 1.0
	v_fma_f32 v114, v114, -2.0, 1.0
	v_fma_f32 v115, v115, -2.0, 1.0
	v_fma_f32 v116, v116, -2.0, 1.0
	v_fma_f32 v117, v117, -2.0, 1.0
	v_add_f32_e32 v110, 1.0, v110
	v_add_f32_e32 v111, 1.0, v111
	v_add_f32_e32 v112, 1.0, v112
	v_add_f32_e32 v113, 1.0, v113
	v_add_f32_e32 v114, 1.0, v114
	v_add_f32_e32 v115, 1.0, v115
	v_add_f32_e32 v116, 1.0, v116
	v_add_f32_e32 v117, 1.0, v117
	v_mul_f32_e32 v86, v86, v110
	v_mul_f32_e32 v87, v87, v111
	v_mul_f32_e32 v88, v88, v112
	v_mul_f32_e32 v89, v89, v113
	v_mul_f32_e32 v90, v90, v114
	v_mul_f32_e32 v91, v91, v115
	v_mul_f32_e32 v92, v92, v116
	v_mul_f32_e32 v93, v93, v117
	v_mul_f32_e32 v86, v86, v102
	v_mul_f32_e32 v87, v87, v103
	v_mul_f32_e32 v88, v88, v104
	v_mul_f32_e32 v89, v89, v105
	v_mul_f32_e32 v90, v90, v106
	v_mul_f32_e32 v91, v91, v107
	v_mul_f32_e32 v92, v92, v108
	v_mul_f32_e32 v93, v93, v109
	v_cvt_pk_bf16_f32 v86, v86, s0
	v_cvt_pk_bf16_f32 v87, v87, s0
	v_cvt_pk_bf16_f32 v88, v88, s0
	v_cvt_pk_bf16_f32 v89, v89, s0
	v_cvt_pk_bf16_f32 v90, v90, s0
	v_cvt_pk_bf16_f32 v91, v91, s0
	v_cvt_pk_bf16_f32 v92, v92, s0
	v_cvt_pk_bf16_f32 v93, v93, s0
	global_store_short v78, v86, s[52:53]
	global_store_short v79, v87, s[52:53]
	global_store_short v80, v88, s[52:53]
	global_store_short v81, v89, s[52:53]
	global_store_short v82, v90, s[52:53]
	global_store_short v83, v91, s[52:53]
	global_store_short v84, v92, s[52:53]
	global_store_short v85, v93, s[52:53]
	s_add_u32 s50, s50, 0x180000
	s_addc_u32 s51, s51, 0
	s_add_u32 s52, s52, 0x80000
	s_addc_u32 s53, s53, 0
	s_add_u32 s62, s62, 1
	s_cmp_lt_u32 s62, 16
	s_cbranch_scc1 .Lrg_tile
	v_readlane_b32 s0, v246, 7
	s_nop 3
	s_add_i32 s24, s24, s0
	s_cmpk_gt_i32 s24, 0xff
	s_barrier
	s_cbranch_scc1 .LBB0_467
	s_branch .LBB0_324
